# phase 0 load balance: the weight-tile walk starts 64 workgroups later, so workgroups 0-63 (memory-token norm + pool tiles) no longer also own the extra 28th tile
# speedup vs baseline: 1.0061x; 1.0061x over previous
; __device__ __forceinline__ int bid_fresh() { int t = blockIdx.x; asm volatile("" : "+s"(t)); return t; }
; __device__ __forceinline__ void phase0(PP p, unsigned char* shm) {
;     ...
;     for (int it = bid_fresh(); it < DEPTH * C_LAYER; it += gridDim.x) {
;         const int l = it / C_LAYER; int r = it % C_LAYER;
;         if (r < C_IN) { tconv_tile_w(p->in[5] + (size_t)l * D * INW, INW, r / 14, r % 14, (bf16_t*)(ws + WS_WIN) + (size_t)l * INW * D, D, tile, p->in[4] + (size_t)l * D); continue; } r -= C_IN;
;         if (r < C_OUT) { tconv_tile_w(p->in[23] + (size_t)l * D * D, D, r / 8, r % 8, (bf16_t*)(ws + WS_WOUT) + (size_t)l * D * D, D, tile, p->in[22] + (size_t)l * D); continue; } r -= C_OUT;
;         if (r < C_XQ) { tconv_tile_w(p->in[25] + (size_t)l * D * 512, 512, r / 2, r % 2, (bf16_t*)(ws + WS_WXQ) + (size_t)l * 512 * D, D, tile, p->in[24] + (size_t)l * D); continue; } r -= C_XQ;
;         if (r < C_XQ) { tconv_tile_w(p->in[26] + (size_t)l * D * 512, 512, r / 2, r % 2, (bf16_t*)(ws + WS_WKV) + (size_t)(l * 1024) * D, D, tile); continue; } r -= C_XQ;
;         if (r < C_XQ) { tconv_tile_w(p->in[27] + (size_t)l * D * 512, 512, r / 2, r % 2, (bf16_t*)(ws + WS_WKV) + (size_t)(l * 1024 + 512) * D, D, tile); continue; } r -= C_XQ;
;         if (r < C_XO) { tconv_tile_w(p->in[28] + (size_t)l * 512 * D, D, r / 8, r % 8, (bf16_t*)(ws + WS_WXO) + (size_t)l * D * 512, 512, tile); continue; } r -= C_XO;
;         if (r < C_UP) { tconv_tile_w(p->in[30] + (size_t)l * D * DFF, DFF, r / 32, r % 32, (bf16_t*)(ws + WS_WUP) + (size_t)l * DFF * D, D, tile, p->in[29] + (size_t)l * D); continue; } r -= C_UP;
;         if (r < C_DN) { if (l == 0) tconv_tile_w(p->in[31] + (size_t)l * DFF * D, D, r / 8, r % 8, (bf16_t*)(ws + WS_WDN) + (size_t)l * D * DFF, DFF, tile); continue; } r -= C_DN;
;         bf16_t* wsm = (bf16_t*)(ws + WS_WSM) + (size_t)l * 1536 * 512;
;         if (r < C_GLU) { tconv_tile_w(p->in[14] + (size_t)l * 512 * 512, 512, r / 2, r % 2, wsm, 512, tile); continue; } r -= C_GLU;
;         if (r < C_POOL) { const int gi = r >> 2, q = r & 3; tconv_tile(p->in[15] + (size_t)(l * 4 + gi) * 128 * 128, 128, q >> 1, q & 1, wsm + (size_t)(512 + gi * 128) * 512 + gi * 128, 512, tile); continue; } r -= C_POOL;
;         tconv_tile_w(p->in[21] + (size_t)l * 512 * 512, 512, r / 2, r % 2, wsm + (size_t)1024 * 512, 512, tile);
;     }
.LBB0_17:
	s_mov_b64 s[14:15], s[0:1]
	s_load_dwordx2 s[12:13], s[14:15], 0x110
	v_writelane_b32 v254, s26, 2
	s_cmpk_gt_i32 s26, 0x2fbf
	s_cbranch_scc1 .LBB0_71
	s_mov_b32 s27, 0
	s_mov_b32 s28, 0
	s_add_i32 s29, s26, 64
	s_and_b32 s29, s29, 0xff
	s_mov_b32 s63, s66
	s_mov_b32 s64, 0
	s_mov_b32 s65, 4
	s_mov_b32 s84, 0x1763ff
	s_mov_b32 s85, 0xbfe
	v_writelane_b32 v255, 0, 62
